# dil_attn and gla_scan operand loads as plain cached loads (coherence from the grid barrier acquire, as for GEMM operands)
# speedup vs baseline: 1.0245x; 1.0029x over previous
.LBB0_297:
	s_and_b64 s[34:35], s[26:27], exec
	s_cselect_b32 s34, s29, s33
	s_lshl_b32 s34, s34, 1
	s_or_b32 s34, s34, s2
	s_ashr_i32 s35, s34, 31
	s_lshl_b64 s[36:37], s[34:35], 17
	s_lshl_b64 s[34:35], s[34:35], 9
	v_lshl_add_u64 v[18:19], v[16:17], 0, s[36:37]
	v_lshl_add_u64 v[20:21], v[42:43], 0, s[34:35]
	v_lshl_add_u64 v[48:49], v[18:19], 0, v[34:35]
	v_lshl_add_u64 v[50:51], v[18:19], 0, v[36:37]
	v_lshl_add_u64 v[52:53], v[18:19], 0, v[38:39]
	global_load_dword v22, v[20:21], off
	v_lshl_add_u64 v[18:19], v[18:19], 0, v[40:41]
	global_load_dword v132, v[48:49], off
	global_load_dword v134, v[48:49], off offset:64
	global_load_dword v136, v[48:49], off offset:128
	s_nop 0
	global_load_dword v48, v[48:49], off offset:192
	s_nop 0
	global_load_dword v23, v[20:21], off offset:4
	global_load_dword v133, v[50:51], off
	global_load_dword v135, v[50:51], off offset:64
	global_load_dword v137, v[50:51], off offset:128
	global_load_dword v49, v[50:51], off offset:192
	s_nop 0
	global_load_dword v50, v[20:21], off offset:8
	global_load_dword v138, v[52:53], off
	global_load_dword v140, v[52:53], off offset:64
	global_load_dword v142, v[52:53], off offset:128
	s_nop 0
	global_load_dword v52, v[52:53], off offset:192
	s_nop 0
	global_load_dword v51, v[20:21], off offset:12
	global_load_dword v139, v[18:19], off
	global_load_dword v141, v[18:19], off offset:64
	global_load_dword v143, v[18:19], off offset:128
	global_load_dword v53, v[18:19], off offset:192
	s_add_i32 s33, s33, -1
	s_add_i32 s29, s29, 1
	s_cmp_lt_u32 s30, 2
	s_cbranch_scc1 .Lpf_w1
	s_and_b64 s[34:35], s[26:27], exec
	s_cselect_b32 s34, s29, s33
	s_lshl_b32 s34, s34, 1
	s_or_b32 s34, s34, s2
	s_ashr_i32 s35, s34, 31
	s_lshl_b64 s[36:37], s[34:35], 17
	s_lshl_b64 s[34:35], s[34:35], 9
	v_lshl_add_u64 v[160:161], v[16:17], 0, s[36:37]
	v_lshl_add_u64 v[162:163], v[42:43], 0, s[34:35]
	v_lshl_add_u64 v[166:167], v[160:161], 0, v[34:35]
	v_lshl_add_u64 v[168:169], v[160:161], 0, v[36:37]
	v_lshl_add_u64 v[170:171], v[160:161], 0, v[38:39]
	global_load_dword v164, v[162:163], off
	v_lshl_add_u64 v[160:161], v[160:161], 0, v[40:41]
	global_load_dword v172, v[166:167], off
	global_load_dword v174, v[166:167], off offset:64
	global_load_dword v182, v[166:167], off offset:128
	s_nop 0
	global_load_dword v166, v[166:167], off offset:192
	s_nop 0
	global_load_dword v165, v[162:163], off offset:4
	global_load_dword v173, v[168:169], off
	global_load_dword v175, v[168:169], off offset:64
	global_load_dword v183, v[168:169], off offset:128
	global_load_dword v167, v[168:169], off offset:192
	s_nop 0
	global_load_dword v168, v[162:163], off offset:8
	global_load_dword v184, v[170:171], off
	global_load_dword v186, v[170:171], off offset:64
	global_load_dword v188, v[170:171], off offset:128
	s_nop 0
	global_load_dword v170, v[170:171], off offset:192
	s_nop 0
	global_load_dword v169, v[162:163], off offset:12
	global_load_dword v185, v[160:161], off
	global_load_dword v187, v[160:161], off offset:64
	global_load_dword v189, v[160:161], off offset:128
	global_load_dword v171, v[160:161], off offset:192
	s_add_i32 s33, s33, -1
	s_add_i32 s29, s29, 1
	s_cmp_lt_u32 s30, 3
	s_cbranch_scc1 .Lpf_w2
	s_and_b64 s[34:35], s[26:27], exec
	s_cselect_b32 s34, s29, s33
	s_lshl_b32 s34, s34, 1
	s_or_b32 s34, s34, s2
	s_ashr_i32 s35, s34, 31
	s_lshl_b64 s[36:37], s[34:35], 17
	s_lshl_b64 s[34:35], s[34:35], 9
	v_lshl_add_u64 v[190:191], v[16:17], 0, s[36:37]
	v_lshl_add_u64 v[192:193], v[42:43], 0, s[34:35]
	v_lshl_add_u64 v[196:197], v[190:191], 0, v[34:35]
	v_lshl_add_u64 v[198:199], v[190:191], 0, v[36:37]
	v_lshl_add_u64 v[200:201], v[190:191], 0, v[38:39]
	global_load_dword v194, v[192:193], off
	v_lshl_add_u64 v[190:191], v[190:191], 0, v[40:41]
	global_load_dword v214, v[196:197], off
	global_load_dword v216, v[196:197], off offset:64
	global_load_dword v218, v[196:197], off offset:128
	s_nop 0
	global_load_dword v196, v[196:197], off offset:192
	s_nop 0
	global_load_dword v195, v[192:193], off offset:4
	global_load_dword v215, v[198:199], off
	global_load_dword v217, v[198:199], off offset:64
	global_load_dword v219, v[198:199], off offset:128
	global_load_dword v197, v[198:199], off offset:192
	s_nop 0
	global_load_dword v198, v[192:193], off offset:8
	global_load_dword v220, v[200:201], off
	global_load_dword v222, v[200:201], off offset:64
	global_load_dword v224, v[200:201], off offset:128
	s_nop 0
	global_load_dword v200, v[200:201], off offset:192
	s_nop 0
	global_load_dword v199, v[192:193], off offset:12
	global_load_dword v221, v[190:191], off
	global_load_dword v223, v[190:191], off offset:64
	global_load_dword v225, v[190:191], off offset:128
	global_load_dword v201, v[190:191], off offset:192
	s_add_i32 s33, s33, -1
	s_add_i32 s29, s29, 1
	s_waitcnt vmcnt(40)
	v_pk_fma_f32 v[2:3], v[2:3], v[50:51], v[138:139]
	v_pk_fma_f32 v[12:13], v[12:13], v[22:23], v[48:49]
	v_pk_fma_f32 v[10:11], v[10:11], v[50:51], v[142:143]
	v_pk_fma_f32 v[14:15], v[14:15], v[50:51], v[52:53]
	v_pk_fma_f32 v[8:9], v[8:9], v[22:23], v[136:137]
	v_pk_fma_f32 v[6:7], v[6:7], v[50:51], v[140:141]
	v_pk_fma_f32 v[4:5], v[4:5], v[22:23], v[134:135]
	v_pk_fma_f32 v[0:1], v[0:1], v[22:23], v[132:133]
	s_waitcnt vmcnt(20)
	v_pk_fma_f32 v[2:3], v[2:3], v[168:169], v[184:185]
	v_pk_fma_f32 v[12:13], v[12:13], v[164:165], v[166:167]
	v_pk_fma_f32 v[10:11], v[10:11], v[168:169], v[188:189]
	v_pk_fma_f32 v[14:15], v[14:15], v[168:169], v[170:171]
	v_pk_fma_f32 v[8:9], v[8:9], v[164:165], v[182:183]
	v_pk_fma_f32 v[6:7], v[6:7], v[168:169], v[186:187]
	v_pk_fma_f32 v[4:5], v[4:5], v[164:165], v[174:175]
	v_pk_fma_f32 v[0:1], v[0:1], v[164:165], v[172:173]
	s_waitcnt vmcnt(0)
	v_pk_fma_f32 v[2:3], v[2:3], v[198:199], v[220:221]
	v_pk_fma_f32 v[12:13], v[12:13], v[194:195], v[196:197]
	v_pk_fma_f32 v[10:11], v[10:11], v[198:199], v[224:225]
	v_pk_fma_f32 v[14:15], v[14:15], v[198:199], v[200:201]
	v_pk_fma_f32 v[8:9], v[8:9], v[194:195], v[218:219]
	v_pk_fma_f32 v[6:7], v[6:7], v[198:199], v[222:223]
	v_pk_fma_f32 v[4:5], v[4:5], v[194:195], v[216:217]
	v_pk_fma_f32 v[0:1], v[0:1], v[194:195], v[214:215]
	s_add_i32 s30, s30, -3
	s_cmp_eq_u32 s30, 0
	s_cbranch_scc0 .LBB0_297
	s_branch .LBB0_299

.LBB0_299:
	s_and_b64 s[34:35], s[26:27], exec
	s_brev_b32 s29, 16
	s_cselect_b32 s30, s29, 0xa000000
	s_add_u32 s33, s80, s30
	s_addc_u32 s34, s81, 0
	s_lshl_b32 s94, s2, 9
	s_lshl_b32 s30, s3, 10
	v_lshl_add_u64 v[48:49], v[26:27], 0, s[94:95]
	s_lshl_b32 s94, s31, 1
	s_lshl_b32 s2, s31, 2
	s_add_u32 s2, s33, s2
	s_addc_u32 s3, s34, 0
	v_lshl_add_u64 v[16:17], s[2:3], 0, v[176:177]
	v_mov_b32_e32 v47, v177
	s_mov_b32 s29, 0
	v_lshl_add_u64 v[50:51], v[28:29], 0, s[94:95]
	v_cndmask_b32_e64 v132, v59, v31, s[26:27]
	v_cndmask_b32_e64 v133, v60, v54, s[26:27]
	v_cndmask_b32_e64 v134, v62, v61, s[26:27]
	v_cndmask_b32_e64 v135, v64, v63, s[26:27]
	v_cndmask_b32_e64 v136, v66, v65, s[26:27]
	v_cndmask_b32_e64 v137, v68, v67, s[26:27]
	v_cndmask_b32_e64 v138, v70, v69, s[26:27]
	v_cndmask_b32_e64 v139, v72, v71, s[26:27]
	v_cndmask_b32_e64 v140, v74, v73, s[26:27]
	v_cndmask_b32_e64 v141, v76, v75, s[26:27]
	v_cndmask_b32_e64 v142, v78, v77, s[26:27]
	v_cndmask_b32_e64 v143, v80, v79, s[26:27]
	v_cndmask_b32_e64 v144, v82, v81, s[26:27]
	v_cndmask_b32_e64 v145, v84, v83, s[26:27]
	v_cndmask_b32_e64 v146, v86, v85, s[26:27]
	v_cndmask_b32_e64 v147, v88, v87, s[26:27]
	v_cndmask_b32_e64 v148, v90, v89, s[26:27]
	v_cndmask_b32_e64 v149, v91, v55, s[26:27]
	v_cndmask_b32_e64 v150, v93, v92, s[26:27]
	v_cndmask_b32_e64 v151, v95, v94, s[26:27]
	v_cndmask_b32_e64 v152, v97, v96, s[26:27]
	v_cndmask_b32_e64 v153, v99, v98, s[26:27]
	v_cndmask_b32_e64 v154, v101, v100, s[26:27]
	v_cndmask_b32_e64 v155, v103, v102, s[26:27]
	v_cndmask_b32_e64 v156, v105, v104, s[26:27]
	v_lshl_add_u64 v[52:53], v[16:17], 0, v[46:47]
	v_cndmask_b32_e64 v47, v121, v118, s[26:27]
	v_cndmask_b32_e64 v157, v122, v119, s[26:27]
	v_cndmask_b32_e64 v158, v123, v120, s[26:27]
	s_movk_i32 s31, 0x3c0
	s_movk_i32 s94, 0x7fff
	s_cmp_lg_u64 s[26:27], 0
	s_cselect_b32 s2, s29, s31
	s_add_i32 s2, s2, s30
	v_add_u32_e32 v246, s2, v133
	v_mov_b32_e32 v245, 0
	v_add_u32_e32 v247, s2, v149
	s_cmp_lg_u64 s[26:27], 0
	s_cbranch_scc0 .Lsc_bwd_pre
	v_add_u32_e32 v244, 4, v246
	v_lshlrev_b32_e32 v244, 10, v244
	v_lshl_add_u64 v[236:237], v[244:245], 0, v[48:49]
	v_add_u32_e32 v244, 12, v246
	v_lshlrev_b32_e32 v244, 10, v244
	v_lshl_add_u64 v[238:239], v[244:245], 0, v[48:49]
	v_add_u32_e32 v244, 8, v246
	v_lshlrev_b32_e32 v244, 9, v244
	v_lshl_add_u64 v[240:241], v[244:245], 0, v[44:45]
	v_lshlrev_b32_e32 v244, 9, v247
	v_lshl_add_u64 v[242:243], v[244:245], 0, v[50:51]
	global_load_dword v59, v[236:237], off offset:-4096
	global_load_ushort v60, v[240:241], off offset:-4096
	global_load_ushort v61, v[240:241], off offset:-3840
	global_load_dword v62, v[236:237], off offset:-3072
	global_load_ushort v63, v[240:241], off offset:-3584
	global_load_ushort v64, v[240:241], off offset:-3328
	global_load_dword v65, v[236:237], off offset:-2048
	global_load_ushort v66, v[240:241], off offset:-3072
	global_load_ushort v67, v[240:241], off offset:-2816
	global_load_dword v68, v[236:237], off offset:-1024
	global_load_ushort v69, v[240:241], off offset:-2560
	global_load_ushort v70, v[240:241], off offset:-2304
	global_load_dword v71, v[236:237], off
	global_load_ushort v72, v[240:241], off offset:-2048
	global_load_ushort v73, v[240:241], off offset:-1792
	global_load_dword v74, v[236:237], off offset:1024
	global_load_ushort v75, v[240:241], off offset:-1536
	global_load_ushort v76, v[240:241], off offset:-1280
	global_load_dword v77, v[236:237], off offset:2048
	global_load_ushort v78, v[240:241], off offset:-1024
	global_load_ushort v79, v[240:241], off offset:-768
	global_load_dword v80, v[236:237], off offset:3072
	global_load_ushort v81, v[240:241], off offset:-512
	global_load_ushort v82, v[240:241], off offset:-256
	global_load_dword v83, v[238:239], off offset:-4096
	global_load_ushort v84, v[240:241], off
	global_load_ushort v85, v[240:241], off offset:256
	global_load_dword v86, v[238:239], off offset:-3072
	global_load_ushort v87, v[240:241], off offset:512
	global_load_ushort v88, v[240:241], off offset:768
	global_load_dword v89, v[238:239], off offset:-2048
	global_load_ushort v90, v[240:241], off offset:1024
	global_load_ushort v91, v[240:241], off offset:1280
	global_load_dword v92, v[238:239], off offset:-1024
	global_load_ushort v93, v[240:241], off offset:1536
	global_load_ushort v94, v[240:241], off offset:1792
	global_load_dword v95, v[238:239], off
	global_load_ushort v96, v[240:241], off offset:2048
	global_load_ushort v97, v[240:241], off offset:2304
	global_load_dword v98, v[238:239], off offset:1024
	global_load_ushort v99, v[240:241], off offset:2560
	global_load_ushort v100, v[240:241], off offset:2816
	global_load_dword v101, v[238:239], off offset:2048
	global_load_ushort v102, v[240:241], off offset:3072
	global_load_ushort v103, v[240:241], off offset:3328
	global_load_dword v104, v[238:239], off offset:3072
	global_load_ushort v105, v[240:241], off offset:3584
	global_load_ushort v227, v[240:241], off offset:3840
	global_load_ushort v228, v[242:243], off
	global_load_ushort v229, v[242:243], off offset:512
	global_load_ushort v230, v[242:243], off offset:1024
	global_load_ushort v231, v[242:243], off offset:1536
	global_load_ushort v232, v[242:243], off offset:2048
	global_load_ushort v233, v[242:243], off offset:2560
	global_load_ushort v234, v[242:243], off offset:3072
	global_load_ushort v235, v[242:243], off offset:3584
	s_branch .Lsc_done_pre
.Lsc_bwd_pre:
	v_add_u32_e32 v244, -3, v246
	v_lshlrev_b32_e32 v244, 10, v244
	v_lshl_add_u64 v[236:237], v[244:245], 0, v[48:49]
	v_add_u32_e32 v244, -11, v246
	v_lshlrev_b32_e32 v244, 10, v244
	v_lshl_add_u64 v[238:239], v[244:245], 0, v[48:49]
	v_add_u32_e32 v244, -7, v246
	v_lshlrev_b32_e32 v244, 9, v244
	v_lshl_add_u64 v[240:241], v[244:245], 0, v[44:45]
	v_lshlrev_b32_e32 v244, 9, v247
	v_lshl_add_u64 v[242:243], v[244:245], 0, v[50:51]
	global_load_dword v59, v[236:237], off offset:3072
	global_load_ushort v60, v[240:241], off offset:3584
	global_load_ushort v61, v[240:241], off offset:3840
	global_load_dword v62, v[236:237], off offset:2048
	global_load_ushort v63, v[240:241], off offset:3072
	global_load_ushort v64, v[240:241], off offset:3328
	global_load_dword v65, v[236:237], off offset:1024
	global_load_ushort v66, v[240:241], off offset:2560
	global_load_ushort v67, v[240:241], off offset:2816
	global_load_dword v68, v[236:237], off
	global_load_ushort v69, v[240:241], off offset:2048
	global_load_ushort v70, v[240:241], off offset:2304
	global_load_dword v71, v[236:237], off offset:-1024
	global_load_ushort v72, v[240:241], off offset:1536
	global_load_ushort v73, v[240:241], off offset:1792
	global_load_dword v74, v[236:237], off offset:-2048
	global_load_ushort v75, v[240:241], off offset:1024
	global_load_ushort v76, v[240:241], off offset:1280
	global_load_dword v77, v[236:237], off offset:-3072
	global_load_ushort v78, v[240:241], off offset:512
	global_load_ushort v79, v[240:241], off offset:768
	global_load_dword v80, v[236:237], off offset:-4096
	global_load_ushort v81, v[240:241], off
	global_load_ushort v82, v[240:241], off offset:256
	global_load_dword v83, v[238:239], off offset:3072
	global_load_ushort v84, v[240:241], off offset:-512
	global_load_ushort v85, v[240:241], off offset:-256
	global_load_dword v86, v[238:239], off offset:2048
	global_load_ushort v87, v[240:241], off offset:-1024
	global_load_ushort v88, v[240:241], off offset:-768
	global_load_dword v89, v[238:239], off offset:1024
	global_load_ushort v90, v[240:241], off offset:-1536
	global_load_ushort v91, v[240:241], off offset:-1280
	global_load_dword v92, v[238:239], off
	global_load_ushort v93, v[240:241], off offset:-2048
	global_load_ushort v94, v[240:241], off offset:-1792
	global_load_dword v95, v[238:239], off offset:-1024
	global_load_ushort v96, v[240:241], off offset:-2560
	global_load_ushort v97, v[240:241], off offset:-2304
	global_load_dword v98, v[238:239], off offset:-2048
	global_load_ushort v99, v[240:241], off offset:-3072
	global_load_ushort v100, v[240:241], off offset:-2816
	global_load_dword v101, v[238:239], off offset:-3072
	global_load_ushort v102, v[240:241], off offset:-3584
	global_load_ushort v103, v[240:241], off offset:-3328
	global_load_dword v104, v[238:239], off offset:-4096
	global_load_ushort v105, v[240:241], off offset:-4096
	global_load_ushort v227, v[240:241], off offset:-3840
	global_load_ushort v228, v[242:243], off
	global_load_ushort v229, v[242:243], off offset:-512
	global_load_ushort v230, v[242:243], off offset:-1024
	global_load_ushort v231, v[242:243], off offset:-1536
	global_load_ushort v232, v[242:243], off offset:-2048
	global_load_ushort v233, v[242:243], off offset:-2560
	global_load_ushort v234, v[242:243], off offset:-3072
	global_load_ushort v235, v[242:243], off offset:-3584

.LBB0_301:
	s_and_b64 s[2:3], s[26:27], exec
	s_cselect_b32 s33, s29, s31
	s_add_i32 s33, s33, s30
	s_waitcnt vmcnt(8)
	v_mov_b32_e32 v23, v59
	v_mov_b32_e32 v161, v60
	v_mov_b32_e32 v162, v61
	v_mov_b32_e32 v20, v62
	v_mov_b32_e32 v163, v63
	v_mov_b32_e32 v164, v64
	v_mov_b32_e32 v21, v65
	v_mov_b32_e32 v167, v66
	v_mov_b32_e32 v168, v67
	v_mov_b32_e32 v22, v68
	v_mov_b32_e32 v169, v69
	v_mov_b32_e32 v170, v70
	v_mov_b32_e32 v159, v71
	v_mov_b32_e32 v171, v72
	v_mov_b32_e32 v172, v73
	v_mov_b32_e32 v160, v74
	v_mov_b32_e32 v173, v75
	v_mov_b32_e32 v174, v76
	v_mov_b32_e32 v165, v77
	v_mov_b32_e32 v183, v78
	v_mov_b32_e32 v184, v79
	v_mov_b32_e32 v166, v80
	v_mov_b32_e32 v185, v81
	v_mov_b32_e32 v186, v82
	v_mov_b32_e32 v175, v83
	v_mov_b32_e32 v187, v84
	v_mov_b32_e32 v188, v85
	v_mov_b32_e32 v182, v86
	v_mov_b32_e32 v189, v87
	v_mov_b32_e32 v190, v88
	v_mov_b32_e32 v221, v89
	v_mov_b32_e32 v193, v90
	v_mov_b32_e32 v194, v91
	v_mov_b32_e32 v222, v92
	v_mov_b32_e32 v195, v93
	v_mov_b32_e32 v196, v94
	v_mov_b32_e32 v223, v95
	v_mov_b32_e32 v197, v96
	v_mov_b32_e32 v198, v97
	v_mov_b32_e32 v224, v98
	v_mov_b32_e32 v199, v99
	v_mov_b32_e32 v200, v100
	v_mov_b32_e32 v225, v101
	v_mov_b32_e32 v214, v102
	v_mov_b32_e32 v215, v103
	v_mov_b32_e32 v226, v104
	v_mov_b32_e32 v216, v105
	v_mov_b32_e32 v217, v227
	v_mov_b32_e32 v18, v228
	v_mov_b32_e32 v19, v229
	v_mov_b32_e32 v191, v230
	v_mov_b32_e32 v192, v231
	v_mov_b32_e32 v201, v232
	v_mov_b32_e32 v213, v233
	v_mov_b32_e32 v218, v234
	v_mov_b32_e32 v16, v235
	s_cmp_eq_u32 s31, 0
	s_cbranch_scc1 .Lsc_nopf
	s_add_i32 s2, s29, 64
	s_sub_i32 s3, s31, 64
	s_cmp_lg_u64 s[26:27], 0
	s_cselect_b32 s2, s2, s3
	s_add_i32 s2, s2, s30
	v_add_u32_e32 v246, s2, v133
	v_mov_b32_e32 v245, 0
	v_add_u32_e32 v247, s2, v149
	s_cmp_lg_u64 s[26:27], 0
	s_cbranch_scc0 .Lsc_bwd_lp
	v_add_u32_e32 v244, 4, v246
	v_lshlrev_b32_e32 v244, 10, v244
	v_lshl_add_u64 v[236:237], v[244:245], 0, v[48:49]
	v_add_u32_e32 v244, 12, v246
	v_lshlrev_b32_e32 v244, 10, v244
	v_lshl_add_u64 v[238:239], v[244:245], 0, v[48:49]
	v_add_u32_e32 v244, 8, v246
	v_lshlrev_b32_e32 v244, 9, v244
	v_lshl_add_u64 v[240:241], v[244:245], 0, v[44:45]
	v_lshlrev_b32_e32 v244, 9, v247
	v_lshl_add_u64 v[242:243], v[244:245], 0, v[50:51]
	global_load_dword v59, v[236:237], off offset:-4096
	global_load_ushort v60, v[240:241], off offset:-4096
	global_load_ushort v61, v[240:241], off offset:-3840
	global_load_dword v62, v[236:237], off offset:-3072
	global_load_ushort v63, v[240:241], off offset:-3584
	global_load_ushort v64, v[240:241], off offset:-3328
	global_load_dword v65, v[236:237], off offset:-2048
	global_load_ushort v66, v[240:241], off offset:-3072
	global_load_ushort v67, v[240:241], off offset:-2816
	global_load_dword v68, v[236:237], off offset:-1024
	global_load_ushort v69, v[240:241], off offset:-2560
	global_load_ushort v70, v[240:241], off offset:-2304
	global_load_dword v71, v[236:237], off
	global_load_ushort v72, v[240:241], off offset:-2048
	global_load_ushort v73, v[240:241], off offset:-1792
	global_load_dword v74, v[236:237], off offset:1024
	global_load_ushort v75, v[240:241], off offset:-1536
	global_load_ushort v76, v[240:241], off offset:-1280
	global_load_dword v77, v[236:237], off offset:2048
	global_load_ushort v78, v[240:241], off offset:-1024
	global_load_ushort v79, v[240:241], off offset:-768
	global_load_dword v80, v[236:237], off offset:3072
	global_load_ushort v81, v[240:241], off offset:-512
	global_load_ushort v82, v[240:241], off offset:-256
	global_load_dword v83, v[238:239], off offset:-4096
	global_load_ushort v84, v[240:241], off
	global_load_ushort v85, v[240:241], off offset:256
	global_load_dword v86, v[238:239], off offset:-3072
	global_load_ushort v87, v[240:241], off offset:512
	global_load_ushort v88, v[240:241], off offset:768
	global_load_dword v89, v[238:239], off offset:-2048
	global_load_ushort v90, v[240:241], off offset:1024
	global_load_ushort v91, v[240:241], off offset:1280
	global_load_dword v92, v[238:239], off offset:-1024
	global_load_ushort v93, v[240:241], off offset:1536
	global_load_ushort v94, v[240:241], off offset:1792
	global_load_dword v95, v[238:239], off
	global_load_ushort v96, v[240:241], off offset:2048
	global_load_ushort v97, v[240:241], off offset:2304
	global_load_dword v98, v[238:239], off offset:1024
	global_load_ushort v99, v[240:241], off offset:2560
	global_load_ushort v100, v[240:241], off offset:2816
	global_load_dword v101, v[238:239], off offset:2048
	global_load_ushort v102, v[240:241], off offset:3072
	global_load_ushort v103, v[240:241], off offset:3328
	global_load_dword v104, v[238:239], off offset:3072
	global_load_ushort v105, v[240:241], off offset:3584
	global_load_ushort v227, v[240:241], off offset:3840
	global_load_ushort v228, v[242:243], off
	global_load_ushort v229, v[242:243], off offset:512
	global_load_ushort v230, v[242:243], off offset:1024
	global_load_ushort v231, v[242:243], off offset:1536
	global_load_ushort v232, v[242:243], off offset:2048
	global_load_ushort v233, v[242:243], off offset:2560
	global_load_ushort v234, v[242:243], off offset:3072
	global_load_ushort v235, v[242:243], off offset:3584
	s_branch .Lsc_done_lp

.LBB0_309:
	s_and_b32 s98, s18, 7
	s_lshr_b32 s99, s18, 3
	s_lshl_b32 s98, s98, 5
	s_add_i32 s98, s98, s99
	s_ashr_i32 s20, s98, 3
	s_and_b32 s19, s98, 3
	s_bfe_u32 s21, s98, 0x10002
	s_cmp_eq_u32 s21, 0
	s_cselect_b64 s[14:15], -1, 0
	s_lshl_b32 s94, s21, 9
	v_lshl_add_u64 v[38:39], v[20:21], 0, s[94:95]
	s_lshl_b32 s94, s19, 7
	v_mov_b32_e32 v96, 0
	s_mov_b32 s23, 0
	s_lshl_b32 s24, s20, 10
	s_lshl_b32 s22, s19, 6
	v_cndmask_b32_e64 v37, v25, v42, s[14:15]
	v_cndmask_b32_e64 v97, v48, v47, s[14:15]
	v_cndmask_b32_e64 v98, v50, v49, s[14:15]
	v_cndmask_b32_e64 v99, v52, v51, s[14:15]
	v_cndmask_b32_e64 v100, v54, v53, s[14:15]
	v_cndmask_b32_e64 v101, v56, v55, s[14:15]
	v_cndmask_b32_e64 v102, v58, v57, s[14:15]
	v_cndmask_b32_e64 v103, v60, v59, s[14:15]
	v_cndmask_b32_e64 v104, v62, v61, s[14:15]
	v_cndmask_b32_e64 v105, v64, v63, s[14:15]
	v_cndmask_b32_e64 v106, v66, v65, s[14:15]
	v_cndmask_b32_e64 v107, v68, v67, s[14:15]
	v_cndmask_b32_e64 v108, v70, v69, s[14:15]
	v_cndmask_b32_e64 v109, v72, v71, s[14:15]
	v_cndmask_b32_e64 v110, v74, v73, s[14:15]
	v_cndmask_b32_e64 v111, v76, v75, s[14:15]
	v_cndmask_b32_e64 v112, v77, v43, s[14:15]
	v_cndmask_b32_e64 v113, v79, v78, s[14:15]
	v_cndmask_b32_e64 v114, v81, v80, s[14:15]
	v_cndmask_b32_e64 v115, v83, v82, s[14:15]
	v_cndmask_b32_e64 v116, v85, v84, s[14:15]
	s_movk_i32 s25, 0x3c0
	v_mov_b32_e32 v0, 0
	v_mov_b32_e32 v1, v96
	v_mov_b32_e32 v2, v96
	v_mov_b32_e32 v3, v96
	v_mov_b32_e32 v4, 0
	v_mov_b32_e32 v5, v96
	v_mov_b32_e32 v6, v96
	v_mov_b32_e32 v7, v96
	v_mov_b32_e32 v8, 0
	v_mov_b32_e32 v9, v96
	v_mov_b32_e32 v10, v96
	v_mov_b32_e32 v11, v96
	v_mov_b32_e32 v12, 0
	v_mov_b32_e32 v13, v96
	v_mov_b32_e32 v14, v96
	v_mov_b32_e32 v15, v96
	v_cndmask_b32_e64 v117, v87, v86, s[14:15]
	v_cndmask_b32_e64 v118, v89, v88, s[14:15]
	v_cndmask_b32_e64 v119, v91, v90, s[14:15]
	v_lshl_add_u64 v[40:41], v[22:23], 0, s[94:95]
	s_mov_b32 s26, 0xc988000
	s_and_b64 s[2:3], s[14:15], exec
	s_cselect_b32 s2, s23, s25
	s_add_i32 s2, s2, s24
	v_add_u32_e32 v246, s2, v37
	v_mov_b32_e32 v245, 0
	v_add_u32_e32 v247, s2, v112
	v_lshl_add_u64 v[240:241], s[46:47], 0, v[176:177]
	v_add_co_u32_e64 v240, s[16:17], s26, v240
	s_nop 1
	v_addc_co_u32_e64 v241, s[16:17], 0, v241, s[16:17]
	s_cmp_lg_u64 s[14:15], 0
	s_cbranch_scc0 .Lsa_bwd_pre
	v_add_u32_e32 v244, 4, v246
	v_lshlrev_b32_e32 v244, 10, v244
	v_lshl_add_u64 v[236:237], v[244:245], 0, v[38:39]
	v_add_u32_e32 v244, 12, v246
	v_lshlrev_b32_e32 v244, 10, v244
	v_lshl_add_u64 v[238:239], v[244:245], 0, v[38:39]
	v_add_u32_e32 v244, 8, v246
	v_lshlrev_b32_e32 v244, 9, v244
	v_lshl_add_u64 v[240:241], v[244:245], 0, v[240:241]
	v_lshlrev_b32_e32 v244, 9, v247
	v_lshl_add_u64 v[242:243], v[244:245], 0, v[40:41]
	global_load_dword v159, v[236:237], off offset:-4096
	global_load_ushort v160, v[240:241], off offset:-3840
	global_load_dword v161, v[236:237], off offset:-3072
	global_load_ushort v162, v[240:241], off offset:-3328
	global_load_dword v163, v[236:237], off offset:-2048
	global_load_ushort v164, v[240:241], off offset:-2816
	global_load_dword v165, v[236:237], off offset:-1024
	global_load_ushort v166, v[240:241], off offset:-2304
	global_load_dword v167, v[236:237], off
	global_load_ushort v168, v[240:241], off offset:-1792
	global_load_dword v169, v[236:237], off offset:1024
	global_load_ushort v170, v[240:241], off offset:-1280
	global_load_dword v171, v[236:237], off offset:2048
	global_load_ushort v172, v[240:241], off offset:-768
	global_load_dword v173, v[236:237], off offset:3072
	global_load_ushort v174, v[240:241], off offset:-256
	global_load_dword v175, v[238:239], off offset:-4096
	global_load_ushort v182, v[240:241], off offset:256
	global_load_dword v183, v[238:239], off offset:-3072
	global_load_ushort v184, v[240:241], off offset:768
	global_load_dword v185, v[238:239], off offset:-2048
	global_load_ushort v186, v[240:241], off offset:1280
	global_load_dword v187, v[238:239], off offset:-1024
	global_load_ushort v188, v[240:241], off offset:1792
	global_load_dword v189, v[238:239], off
	global_load_ushort v190, v[240:241], off offset:2304
	global_load_dword v191, v[238:239], off offset:1024
	global_load_ushort v192, v[240:241], off offset:2816
	global_load_dword v193, v[238:239], off offset:2048
	global_load_ushort v194, v[240:241], off offset:3328
	global_load_dword v195, v[238:239], off offset:3072
	global_load_ushort v196, v[240:241], off offset:3840
	global_load_ushort v197, v[242:243], off
	global_load_ushort v198, v[242:243], off offset:512
	global_load_ushort v199, v[242:243], off offset:1024
	global_load_ushort v200, v[242:243], off offset:1536
	global_load_ushort v201, v[242:243], off offset:2048
	global_load_ushort v213, v[242:243], off offset:2560
	global_load_ushort v214, v[242:243], off offset:3072
	global_load_ushort v215, v[242:243], off offset:3584
	s_branch .Lsa_done_pre
.Lsa_bwd_pre:
	v_add_u32_e32 v244, -3, v246
	v_lshlrev_b32_e32 v244, 10, v244
	v_lshl_add_u64 v[236:237], v[244:245], 0, v[38:39]
	v_add_u32_e32 v244, -11, v246
	v_lshlrev_b32_e32 v244, 10, v244
	v_lshl_add_u64 v[238:239], v[244:245], 0, v[38:39]
	v_add_u32_e32 v244, -7, v246
	v_lshlrev_b32_e32 v244, 9, v244
	v_lshl_add_u64 v[240:241], v[244:245], 0, v[240:241]
	v_lshlrev_b32_e32 v244, 9, v247
	v_lshl_add_u64 v[242:243], v[244:245], 0, v[40:41]
	global_load_dword v159, v[236:237], off offset:3072
	global_load_ushort v160, v[240:241], off offset:3840
	global_load_dword v161, v[236:237], off offset:2048
	global_load_ushort v162, v[240:241], off offset:3328
	global_load_dword v163, v[236:237], off offset:1024
	global_load_ushort v164, v[240:241], off offset:2816
	global_load_dword v165, v[236:237], off
	global_load_ushort v166, v[240:241], off offset:2304
	global_load_dword v167, v[236:237], off offset:-1024
	global_load_ushort v168, v[240:241], off offset:1792
	global_load_dword v169, v[236:237], off offset:-2048
	global_load_ushort v170, v[240:241], off offset:1280
	global_load_dword v171, v[236:237], off offset:-3072
	global_load_ushort v172, v[240:241], off offset:768
	global_load_dword v173, v[236:237], off offset:-4096
	global_load_ushort v174, v[240:241], off offset:256
	global_load_dword v175, v[238:239], off offset:3072
	global_load_ushort v182, v[240:241], off offset:-256
	global_load_dword v183, v[238:239], off offset:2048
	global_load_ushort v184, v[240:241], off offset:-768
	global_load_dword v185, v[238:239], off offset:1024
	global_load_ushort v186, v[240:241], off offset:-1280
	global_load_dword v187, v[238:239], off
	global_load_ushort v188, v[240:241], off offset:-1792
	global_load_dword v189, v[238:239], off offset:-1024
	global_load_ushort v190, v[240:241], off offset:-2304
	global_load_dword v191, v[238:239], off offset:-2048
	global_load_ushort v192, v[240:241], off offset:-2816
	global_load_dword v193, v[238:239], off offset:-3072
	global_load_ushort v194, v[240:241], off offset:-3328
	global_load_dword v195, v[238:239], off offset:-4096
	global_load_ushort v196, v[240:241], off offset:-3840
	global_load_ushort v197, v[242:243], off
	global_load_ushort v198, v[242:243], off offset:-512
	global_load_ushort v199, v[242:243], off offset:-1024
	global_load_ushort v200, v[242:243], off offset:-1536
	global_load_ushort v201, v[242:243], off offset:-2048
	global_load_ushort v213, v[242:243], off offset:-2560
	global_load_ushort v214, v[242:243], off offset:-3072
	global_load_ushort v215, v[242:243], off offset:-3584

.LBB0_311:
	s_waitcnt vmcnt(0)
	v_mov_b32_e32 v120, v159
	v_mov_b32_e32 v121, v160
	v_mov_b32_e32 v124, v161
	v_mov_b32_e32 v122, v162
	v_mov_b32_e32 v125, v163
	v_mov_b32_e32 v123, v164
	v_mov_b32_e32 v127, v165
	v_mov_b32_e32 v126, v166
	v_mov_b32_e32 v129, v167
	v_mov_b32_e32 v128, v168
	v_mov_b32_e32 v130, v169
	v_mov_b32_e32 v131, v170
	v_mov_b32_e32 v134, v171
	v_mov_b32_e32 v132, v172
	v_mov_b32_e32 v135, v173
	v_mov_b32_e32 v133, v174
	v_mov_b32_e32 v138, v175
	v_mov_b32_e32 v136, v182
	v_mov_b32_e32 v139, v183
	v_mov_b32_e32 v137, v184
	v_mov_b32_e32 v153, v185
	v_mov_b32_e32 v140, v186
	v_mov_b32_e32 v154, v187
	v_mov_b32_e32 v141, v188
	v_mov_b32_e32 v155, v189
	v_mov_b32_e32 v142, v190
	v_mov_b32_e32 v156, v191
	v_mov_b32_e32 v145, v192
	v_mov_b32_e32 v157, v193
	v_mov_b32_e32 v146, v194
	v_mov_b32_e32 v158, v195
	v_mov_b32_e32 v149, v196
	v_mov_b32_e32 v18, v197
	v_mov_b32_e32 v19, v198
	v_mov_b32_e32 v143, v199
	v_mov_b32_e32 v144, v200
	v_mov_b32_e32 v147, v201
	v_mov_b32_e32 v148, v213
	v_mov_b32_e32 v150, v214
	v_mov_b32_e32 v16, v215
	s_cmp_eq_u32 s25, 0
	s_cbranch_scc1 .Lsa_nopf
	s_add_i32 s16, s23, 64
	s_sub_i32 s17, s25, 64
	s_and_b64 s[2:3], s[14:15], exec
	s_cselect_b32 s2, s16, s17
	s_add_i32 s2, s2, s24
	v_add_u32_e32 v246, s2, v37
	v_mov_b32_e32 v245, 0
	v_add_u32_e32 v247, s2, v112
	v_lshl_add_u64 v[240:241], s[46:47], 0, v[176:177]
	v_add_co_u32_e64 v240, s[16:17], s26, v240
	s_nop 1
	v_addc_co_u32_e64 v241, s[16:17], 0, v241, s[16:17]
	s_cmp_lg_u64 s[14:15], 0
	s_cbranch_scc0 .Lsa_bwd_lp
	v_add_u32_e32 v244, 4, v246
	v_lshlrev_b32_e32 v244, 10, v244
	v_lshl_add_u64 v[236:237], v[244:245], 0, v[38:39]
	v_add_u32_e32 v244, 12, v246
	v_lshlrev_b32_e32 v244, 10, v244
	v_lshl_add_u64 v[238:239], v[244:245], 0, v[38:39]
	v_add_u32_e32 v244, 8, v246
	v_lshlrev_b32_e32 v244, 9, v244
	v_lshl_add_u64 v[240:241], v[244:245], 0, v[240:241]
	v_lshlrev_b32_e32 v244, 9, v247
	v_lshl_add_u64 v[242:243], v[244:245], 0, v[40:41]
	global_load_dword v159, v[236:237], off offset:-4096
	global_load_ushort v160, v[240:241], off offset:-3840
	global_load_dword v161, v[236:237], off offset:-3072
	global_load_ushort v162, v[240:241], off offset:-3328
	global_load_dword v163, v[236:237], off offset:-2048
	global_load_ushort v164, v[240:241], off offset:-2816
	global_load_dword v165, v[236:237], off offset:-1024
	global_load_ushort v166, v[240:241], off offset:-2304
	global_load_dword v167, v[236:237], off
	global_load_ushort v168, v[240:241], off offset:-1792
	global_load_dword v169, v[236:237], off offset:1024
	global_load_ushort v170, v[240:241], off offset:-1280
	global_load_dword v171, v[236:237], off offset:2048
	global_load_ushort v172, v[240:241], off offset:-768
	global_load_dword v173, v[236:237], off offset:3072
	global_load_ushort v174, v[240:241], off offset:-256
	global_load_dword v175, v[238:239], off offset:-4096
	global_load_ushort v182, v[240:241], off offset:256
	global_load_dword v183, v[238:239], off offset:-3072
	global_load_ushort v184, v[240:241], off offset:768
	global_load_dword v185, v[238:239], off offset:-2048
	global_load_ushort v186, v[240:241], off offset:1280
	global_load_dword v187, v[238:239], off offset:-1024
	global_load_ushort v188, v[240:241], off offset:1792
	global_load_dword v189, v[238:239], off
	global_load_ushort v190, v[240:241], off offset:2304
	global_load_dword v191, v[238:239], off offset:1024
	global_load_ushort v192, v[240:241], off offset:2816
	global_load_dword v193, v[238:239], off offset:2048
	global_load_ushort v194, v[240:241], off offset:3328
	global_load_dword v195, v[238:239], off offset:3072
	global_load_ushort v196, v[240:241], off offset:3840
	global_load_ushort v197, v[242:243], off
	global_load_ushort v198, v[242:243], off offset:512
	global_load_ushort v199, v[242:243], off offset:1024
	global_load_ushort v200, v[242:243], off offset:1536
	global_load_ushort v201, v[242:243], off offset:2048
	global_load_ushort v213, v[242:243], off offset:2560
	global_load_ushort v214, v[242:243], off offset:3072
	global_load_ushort v215, v[242:243], off offset:3584
	s_branch .Lsa_done_lp
